# v30 plus SWA sample-unit staging de-serialised (10 loads in flight, one wait, on the phase-2 tail)
# baseline (speedup 1.0000x reference)
; #define LAS __attribute__((address_space(3)))
; DI void swa_stage_sample(const Params& p, lptr L, const SwaU& u, int tid) {
;     const bf16_t* P = (const bf16_t*)(p.ws + WS_P);
; #pragma unroll 1
;     for (int k = 0; k < 3; ++k) { const int c = tid + 512 * k, row = c >> 3, cc = c & 7; u32x4 kv, vv;
;         if (row < 128) { const size_t o = ((size_t)(u.b * 128 + row) * 2 + u.kvh) * 64 + cc * 8;
;     ...
;         else { const bf16_t* src = P + G_SKV + (size_t)(u.row0 - 128 + row) * 256 + u.kvh * 64 + cc * 8; kv = *(const u32x4*)src; vv = *(const u32x4*)(src + 128); }
;         *(LAS u32x4*)(L + S_KS + row * VP + cc * 16) = kv; *(LAS u32x4*)(L + S_VS + row * VP2 + cc * 16) = vv; }
; }
.LBB0_585:
	s_and_b64 vcc, exec, s[4:5]
	s_cbranch_vccz .LBB0_596
	s_lshl_b32 s76, s9, 7
	v_lshl_add_u64 v[16:17], v[32:33], 0, s[76:77]
	v_lshl_or_b32 v18, s9, 6, v111
	v_lshl_or_b32 v19, s7, 7, v31
	v_add_u32_e32 v20, s8, v106
	s_mov_b32 s4, 0
	v_mov_b32_e32 v21, v147
	v_mov_b32_e32 v22, v146
	v_mov_b32_e32 v23, v153
	v_mov_b32_e32 v180, v19
	v_ashrrev_i32_e32 v181, 31, v180
	v_lshlrev_b64 v[180:181], 9, v[180:181]
	v_lshl_or_b32 v180, v18, 2, v180
	v_lshl_add_u64 v[182:183], s[78:79], 0, v[180:181]
	v_lshl_add_u64 v[184:185], s[80:81], 0, v[180:181]
	global_load_dwordx4 v[200:203], v[182:183], off
	global_load_dwordx4 v[204:207], v[182:183], off offset:16
	global_load_dwordx4 v[208:211], v[184:185], off
	global_load_dwordx4 v[212:215], v[184:185], off offset:16
	v_add_u32_e32 v186, 64, v19
	v_ashrrev_i32_e32 v187, 31, v186
	v_lshlrev_b64 v[186:187], 9, v[186:187]
	v_lshl_or_b32 v186, v18, 2, v186
	v_lshl_add_u64 v[188:189], s[78:79], 0, v[186:187]
	v_lshl_add_u64 v[190:191], s[80:81], 0, v[186:187]
	global_load_dwordx4 v[216:219], v[188:189], off
	global_load_dwordx4 v[220:223], v[188:189], off offset:16
	global_load_dwordx4 v[224:227], v[190:191], off
	global_load_dwordx4 v[228:231], v[190:191], off offset:16
	v_add_u32_e32 v192, 0x80, v20
	v_ashrrev_i32_e32 v193, 31, v192
	v_lshlrev_b64 v[192:193], 9, v[192:193]
	v_lshl_add_u64 v[194:195], v[16:17], 0, v[192:193]
	global_load_dwordx4 v[232:235], v[194:195], off
	global_load_dwordx4 v[236:239], v[194:195], off offset:256
	s_waitcnt vmcnt(0)
	v_cvt_pk_bf16_f32 v200, v200, v201
	v_cvt_pk_bf16_f32 v201, v202, v203
	v_cvt_pk_bf16_f32 v202, v204, v205
	v_cvt_pk_bf16_f32 v203, v206, v207
	v_cvt_pk_bf16_f32 v208, v208, v209
	v_cvt_pk_bf16_f32 v209, v210, v211
	v_cvt_pk_bf16_f32 v210, v212, v213
	v_cvt_pk_bf16_f32 v211, v214, v215
	v_cvt_pk_bf16_f32 v216, v216, v217
	v_cvt_pk_bf16_f32 v217, v218, v219
	v_cvt_pk_bf16_f32 v218, v220, v221
	v_cvt_pk_bf16_f32 v219, v222, v223
	v_cvt_pk_bf16_f32 v224, v224, v225
	v_cvt_pk_bf16_f32 v225, v226, v227
	v_cvt_pk_bf16_f32 v226, v228, v229
	v_cvt_pk_bf16_f32 v227, v230, v231
	ds_write_b128 v147, v[200:203]
	ds_write_b128 v146, v[208:211]
	ds_write_b128 v147, v[216:219] offset:9216
	ds_write_b128 v146, v[224:227] offset:10240
	ds_write_b128 v147, v[232:235] offset:18432
	ds_write_b128 v146, v[236:239] offset:20480
	s_movk_i32 s4, 0xc0
	v_add_u32_e32 v23, 0x600, v153
	v_add_u32_e32 v22, 0x7800, v146
	v_add_u32_e32 v21, 0x6c00, v147
	s_branch .LBB0_595
